# stack: flat grid barrier after prologue + unrolled zb cast loop + GBAR non-leaders poll top generation word
# speedup vs baseline: 1.0012x; 1.0012x over previous
; DEVI unsigned pk2(float lo, float hi) { unsigned r; asm("v_cvt_pk_bf16_f32 %0, %1, %2" : "=v"(r) : "v"(lo), "v"(hi)); return r; }
; DEVI void phase_prologue(const Params& p, unsigned char* smem) {
;     ...
;     for (size_t i = gt; i < (size_t)MROWS * DM / 8; i += gn) {
;         const f32x4 a = ((const f32x4*)p.in[0])[2 * i], b = ((const f32x4*)p.in[0])[2 * i + 1];
;         u32x4 o; o.x = pk2(a[0], a[1]); o.y = pk2(a[2], a[3]); o.z = pk2(b[0], b[1]); o.w = pk2(b[2], b[3]);
;         ((u32x4*)(ws + WS_ZB))[i] = o;
;     }
.LBB0_117:
	s_or_b64 exec, exec, s[2:3]
	s_mov_b64 s[0:1], 0x400000
	v_cmp_gt_u64_e32 vcc, s[0:1], v[6:7]
	s_and_saveexec_b64 s[0:1], vcc
	s_cbranch_execz .LBB0_120
	s_lshl_b64 s[2:3], s[44:45], 13
	s_add_u32 s2, s96, s2
	s_addc_u32 s3, s97, s3
	v_readlane_b32 s12, v249, 5
	s_waitcnt vmcnt(0)
	v_lshl_add_u64 v[2:3], v[26:27], 4, s[2:3]
	s_mov_b64 s[2:3], 0x6800000
	v_readlane_b32 s13, v249, 6
	v_lshl_add_u64 v[2:3], v[2:3], 0, s[2:3]
	s_lshl_b64 s[2:3], s[6:7], 13
	s_lshl_b64 s[4:5], s[44:45], 14
	s_mov_b64 s[8:9], s[12:13]
	s_add_u32 s4, s8, s4
	v_lshlrev_b64 v[4:5], 5, v[26:27]
	s_addc_u32 s5, s9, s5
	v_lshl_add_u64 v[4:5], s[4:5], 0, v[4:5]
	v_lshl_add_u64 v[4:5], v[4:5], 0, 16
	s_lshl_b64 s[4:5], s[6:7], 14
	s_mov_b64 s[6:7], 0
	s_mov_b64 s[8:9], 0x3fffff
	v_readlane_b32 s14, v249, 7
	v_readlane_b32 s15, v249, 8
	v_readlane_b32 s16, v249, 9
	v_readlane_b32 s17, v249, 10
	v_readlane_b32 s18, v249, 11
	v_readlane_b32 s19, v249, 12
	v_readlane_b32 s20, v249, 13
	v_readlane_b32 s21, v249, 14
	v_readlane_b32 s22, v249, 15
	v_readlane_b32 s23, v249, 16
	v_readlane_b32 s24, v249, 17
	v_readlane_b32 s25, v249, 18
	v_readlane_b32 s26, v249, 19
	v_readlane_b32 s27, v249, 20
	s_cmp_lg_u32 s10, 0x20000
	s_cbranch_scc1 .LBB0_119
	s_cmp_lg_u32 s11, 0
	s_cbranch_scc1 .LBB0_119
	s_movk_i32 s98, 8
.Lzb_fast:
	global_load_dwordx4 v[8:11], v[4:5], off offset:-16
	global_load_dwordx4 v[12:15], v[4:5], off
	v_lshl_add_u64 v[4:5], v[4:5], 0, s[4:5]
	global_load_dwordx4 v[16:19], v[4:5], off offset:-16
	global_load_dwordx4 v[20:23], v[4:5], off
	v_lshl_add_u64 v[4:5], v[4:5], 0, s[4:5]
	global_load_dwordx4 v[24:27], v[4:5], off offset:-16
	global_load_dwordx4 v[28:31], v[4:5], off
	v_lshl_add_u64 v[4:5], v[4:5], 0, s[4:5]
	global_load_dwordx4 v[32:35], v[4:5], off offset:-16
	global_load_dwordx4 v[36:39], v[4:5], off
	v_lshl_add_u64 v[4:5], v[4:5], 0, s[4:5]
	s_waitcnt vmcnt(6)
	v_cvt_pk_bf16_f32 v8, v8, v9
	v_cvt_pk_bf16_f32 v9, v10, v11
	v_cvt_pk_bf16_f32 v10, v12, v13
	v_cvt_pk_bf16_f32 v11, v14, v15
	global_store_dwordx4 v[2:3], v[8:11], off
	v_lshl_add_u64 v[2:3], v[2:3], 0, s[2:3]
	s_waitcnt vmcnt(5)
	v_cvt_pk_bf16_f32 v16, v16, v17
	v_cvt_pk_bf16_f32 v17, v18, v19
	v_cvt_pk_bf16_f32 v18, v20, v21
	v_cvt_pk_bf16_f32 v19, v22, v23
	global_store_dwordx4 v[2:3], v[16:19], off
	v_lshl_add_u64 v[2:3], v[2:3], 0, s[2:3]
	s_waitcnt vmcnt(4)
	v_cvt_pk_bf16_f32 v24, v24, v25
	v_cvt_pk_bf16_f32 v25, v26, v27
	v_cvt_pk_bf16_f32 v26, v28, v29
	v_cvt_pk_bf16_f32 v27, v30, v31
	global_store_dwordx4 v[2:3], v[24:27], off
	v_lshl_add_u64 v[2:3], v[2:3], 0, s[2:3]
	s_waitcnt vmcnt(3)
	v_cvt_pk_bf16_f32 v32, v32, v33
	v_cvt_pk_bf16_f32 v33, v34, v35
	v_cvt_pk_bf16_f32 v34, v36, v37
	v_cvt_pk_bf16_f32 v35, v38, v39
	global_store_dwordx4 v[2:3], v[32:35], off
	v_lshl_add_u64 v[2:3], v[2:3], 0, s[2:3]
	s_sub_u32 s98, s98, 1
	s_cmp_lg_u32 s98, 0
	s_cbranch_scc1 .Lzb_fast
	s_branch .LBB0_120

; DEVI unsigned xb_ld(unsigned* p)              { return __hip_atomic_load(p, __ATOMIC_RELAXED, __HIP_MEMORY_SCOPE_AGENT); }
; DEVI unsigned xb_add(unsigned* p, unsigned v) { return __hip_atomic_fetch_add(p, v, __ATOMIC_RELAXED, __HIP_MEMORY_SCOPE_AGENT); }
; #define XB_SPIN(cond, bar) do { unsigned _sp = 0; while (cond) { __builtin_amdgcn_s_sleep(1); \
;     if ((++_sp & 255u) == 0u) { if (xb_ld(&(bar)[XB_TMO])) break; if (_sp > XB_SPIN_CAP) { atomicAdd(&(bar)[XB_TMO], 1u); break; } } } } while (0)
; DEVI void xcd_barrier(unsigned* bar, volatile LAS unsigned* st) {
;     ...
;         const unsigned old = xb_add(&bar[XB_XSUB(x)], 1u);
;         const unsigned gen = old / nloc;
;         if (old + 1u == (gen + 1u) * nloc) {
;             __builtin_amdgcn_fence(__ATOMIC_RELEASE, "agent");
;             asm volatile("s_waitcnt vmcnt(0)" ::: "memory");
;             const unsigned og = xb_add(&bar[XB_TOP], 1u);
;             const unsigned tg = og / nx;
;             if (og + 1u == (tg + 1u) * nx) xb_add(&bar[XB_TOPGEN], 1u);
;             else XB_SPIN(xb_ld(&bar[XB_TOPGEN]) == tg, bar);
;             __builtin_amdgcn_fence(__ATOMIC_ACQUIRE, "agent");
;             xb_add(&bar[XB_XGEN(x)], 1u);
;             asm volatile("s_waitcnt vmcnt(0)" ::: "memory");
;         } else {
;             XB_SPIN(xb_ld(&bar[XB_XGEN(x)]) == gen, bar);
.LBB0_164:
	s_or_b64 exec, exec, s[6:7]
	v_cvt_f32_u32_e32 v4, v2
	s_waitcnt vmcnt(0)
	v_readfirstlane_b32 s4, v3
	v_sub_u32_e32 v3, 0, v2
	v_rcp_iflag_f32_e32 v4, v4
	v_add_u32_e32 v5, s4, v1
	v_mul_f32_e32 v4, 0x4f7ffffe, v4
	v_cvt_u32_f32_e32 v4, v4
	v_mul_lo_u32 v1, v3, v4
	v_mul_hi_u32 v1, v4, v1
	v_add_u32_e32 v1, v4, v1
	v_mul_hi_u32 v1, v5, v1
	v_mul_lo_u32 v3, v1, v2
	v_sub_u32_e32 v3, v5, v3
	v_add_u32_e32 v4, 1, v1
	v_cmp_ge_u32_e32 vcc, v3, v2
	s_nop 1
	v_cndmask_b32_e32 v1, v1, v4, vcc
	v_sub_u32_e32 v4, v3, v2
	v_cndmask_b32_e32 v3, v3, v4, vcc
	v_add_u32_e32 v4, 1, v1
	v_cmp_ge_u32_e32 vcc, v3, v2
	v_add_u32_e32 v3, 1, v5
	s_nop 0
	v_cndmask_b32_e32 v1, v1, v4, vcc
	v_mul_lo_u32 v4, v2, v1
	v_add_u32_e32 v2, v4, v2
	v_cmp_ne_u32_e32 vcc, v3, v2
	s_and_saveexec_b64 s[4:5], vcc
	s_xor_b64 s[4:5], exec, s[4:5]
	s_cbranch_execz .LBB0_182
	s_waitcnt lgkmcnt(0)
	s_add_u32 s10, s96, 0x6ff500
	s_addc_u32 s11, s97, 0
	v_mov_b32_e32 v0, 0
	global_load_dword v0, v0, s[10:11] sc1
	s_waitcnt vmcnt(0)
	v_cmp_eq_u32_e32 vcc, v0, v1
	s_and_saveexec_b64 s[6:7], vcc
	s_cbranch_execz .LBB0_181
	s_add_u32 s8, s96, 0x6fc200
	s_addc_u32 s9, s97, 0
	s_mov_b32 s22, 1
	s_mov_b64 s[12:13], 0
	v_mov_b32_e32 v0, 0
	s_branch .LBB0_168

; DEVI unsigned xb_ld(unsigned* p)              { return __hip_atomic_load(p, __ATOMIC_RELAXED, __HIP_MEMORY_SCOPE_AGENT); }
; DEVI unsigned xb_add(unsigned* p, unsigned v) { return __hip_atomic_fetch_add(p, v, __ATOMIC_RELAXED, __HIP_MEMORY_SCOPE_AGENT); }
; #define XB_SPIN(cond, bar) do { unsigned _sp = 0; while (cond) { __builtin_amdgcn_s_sleep(1); \
;     if ((++_sp & 255u) == 0u) { if (xb_ld(&(bar)[XB_TMO])) break; if (_sp > XB_SPIN_CAP) { atomicAdd(&(bar)[XB_TMO], 1u); break; } } } } while (0)
; DEVI void xcd_barrier(unsigned* bar, volatile LAS unsigned* st) {
;     ...
;         const unsigned old = xb_add(&bar[XB_XSUB(x)], 1u);
;         const unsigned gen = old / nloc;
;         if (old + 1u == (gen + 1u) * nloc) {
;             __builtin_amdgcn_fence(__ATOMIC_RELEASE, "agent");
;             asm volatile("s_waitcnt vmcnt(0)" ::: "memory");
;             const unsigned og = xb_add(&bar[XB_TOP], 1u);
;             const unsigned tg = og / nx;
;             if (og + 1u == (tg + 1u) * nx) xb_add(&bar[XB_TOPGEN], 1u);
;             else XB_SPIN(xb_ld(&bar[XB_TOPGEN]) == tg, bar);
;             __builtin_amdgcn_fence(__ATOMIC_ACQUIRE, "agent");
;             xb_add(&bar[XB_XGEN(x)], 1u);
;             asm volatile("s_waitcnt vmcnt(0)" ::: "memory");
;         } else {
;             XB_SPIN(xb_ld(&bar[XB_XGEN(x)]) == gen, bar);
.LBB0_1461:
	s_or_b64 exec, exec, s[8:9]
	v_cvt_f32_u32_e32 v4, v2
	s_waitcnt vmcnt(0)
	v_readfirstlane_b32 s6, v3
	v_sub_u32_e32 v3, 0, v2
	v_rcp_iflag_f32_e32 v4, v4
	v_add_u32_e32 v5, s6, v1
	v_mul_f32_e32 v4, 0x4f7ffffe, v4
	v_cvt_u32_f32_e32 v4, v4
	v_mul_lo_u32 v1, v3, v4
	v_mul_hi_u32 v1, v4, v1
	v_add_u32_e32 v1, v4, v1
	v_mul_hi_u32 v1, v5, v1
	v_mul_lo_u32 v3, v1, v2
	v_sub_u32_e32 v3, v5, v3
	v_add_u32_e32 v4, 1, v1
	v_cmp_ge_u32_e32 vcc, v3, v2
	s_nop 1
	v_cndmask_b32_e32 v1, v1, v4, vcc
	v_sub_u32_e32 v4, v3, v2
	v_cndmask_b32_e32 v3, v3, v4, vcc
	v_add_u32_e32 v4, 1, v1
	v_cmp_ge_u32_e32 vcc, v3, v2
	v_add_u32_e32 v3, 1, v5
	s_nop 0
	v_cndmask_b32_e32 v1, v1, v4, vcc
	v_mul_lo_u32 v4, v2, v1
	v_add_u32_e32 v2, v4, v2
	v_cmp_ne_u32_e32 vcc, v3, v2
	s_and_saveexec_b64 s[6:7], vcc
	s_xor_b64 s[6:7], exec, s[6:7]
	s_cbranch_execz .LBB0_1475
	s_waitcnt lgkmcnt(0)
	s_add_u32 s12, s96, 0x6ff500
	s_addc_u32 s13, s97, 0
	v_mov_b32_e32 v0, 0
	global_load_dword v0, v0, s[12:13] sc1
	s_waitcnt vmcnt(0)
	v_cmp_eq_u32_e32 vcc, v0, v1
	s_and_saveexec_b64 s[8:9], vcc
	s_cbranch_execz .LBB0_1474
	s_add_u32 s10, s96, 0x6fc200
	s_addc_u32 s11, s97, 0
	s_mov_b32 s24, 1
	s_mov_b64 s[14:15], 0
	v_mov_b32_e32 v0, 0
	s_branch .LBB0_1465

; DEVI unsigned xb_ld(unsigned* p)              { return __hip_atomic_load(p, __ATOMIC_RELAXED, __HIP_MEMORY_SCOPE_AGENT); }
; DEVI unsigned xb_add(unsigned* p, unsigned v) { return __hip_atomic_fetch_add(p, v, __ATOMIC_RELAXED, __HIP_MEMORY_SCOPE_AGENT); }
; #define XB_SPIN(cond, bar) do { unsigned _sp = 0; while (cond) { __builtin_amdgcn_s_sleep(1); \
;     if ((++_sp & 255u) == 0u) { if (xb_ld(&(bar)[XB_TMO])) break; if (_sp > XB_SPIN_CAP) { atomicAdd(&(bar)[XB_TMO], 1u); break; } } } } while (0)
; DEVI void xcd_barrier(unsigned* bar, volatile LAS unsigned* st) {
;     ...
;         const unsigned old = xb_add(&bar[XB_XSUB(x)], 1u);
;         const unsigned gen = old / nloc;
;         if (old + 1u == (gen + 1u) * nloc) {
;             __builtin_amdgcn_fence(__ATOMIC_RELEASE, "agent");
;             asm volatile("s_waitcnt vmcnt(0)" ::: "memory");
;             const unsigned og = xb_add(&bar[XB_TOP], 1u);
;             const unsigned tg = og / nx;
;             if (og + 1u == (tg + 1u) * nx) xb_add(&bar[XB_TOPGEN], 1u);
;             else XB_SPIN(xb_ld(&bar[XB_TOPGEN]) == tg, bar);
;             __builtin_amdgcn_fence(__ATOMIC_ACQUIRE, "agent");
;             xb_add(&bar[XB_XGEN(x)], 1u);
;             asm volatile("s_waitcnt vmcnt(0)" ::: "memory");
;         } else {
;             XB_SPIN(xb_ld(&bar[XB_XGEN(x)]) == gen, bar);
.LBB0_2768:
	s_or_b64 exec, exec, s[6:7]
	v_cvt_f32_u32_e32 v4, v2
	s_waitcnt vmcnt(0)
	v_readfirstlane_b32 s4, v3
	v_sub_u32_e32 v3, 0, v2
	v_rcp_iflag_f32_e32 v4, v4
	v_add_u32_e32 v5, s4, v1
	v_mul_f32_e32 v4, 0x4f7ffffe, v4
	v_cvt_u32_f32_e32 v4, v4
	v_mul_lo_u32 v1, v3, v4
	v_mul_hi_u32 v1, v4, v1
	v_add_u32_e32 v1, v4, v1
	v_mul_hi_u32 v1, v5, v1
	v_mul_lo_u32 v3, v1, v2
	v_sub_u32_e32 v3, v5, v3
	v_add_u32_e32 v4, 1, v1
	v_cmp_ge_u32_e32 vcc, v3, v2
	s_nop 1
	v_cndmask_b32_e32 v1, v1, v4, vcc
	v_sub_u32_e32 v4, v3, v2
	v_cndmask_b32_e32 v3, v3, v4, vcc
	v_add_u32_e32 v4, 1, v1
	v_cmp_ge_u32_e32 vcc, v3, v2
	v_add_u32_e32 v3, 1, v5
	s_nop 0
	v_cndmask_b32_e32 v1, v1, v4, vcc
	v_mul_lo_u32 v4, v2, v1
	v_add_u32_e32 v2, v4, v2
	v_cmp_ne_u32_e32 vcc, v3, v2
	s_and_saveexec_b64 s[4:5], vcc
	s_xor_b64 s[4:5], exec, s[4:5]
	s_cbranch_execz .LBB0_2782
	s_waitcnt lgkmcnt(0)
	s_add_u32 s10, s96, 0x6ff500
	s_addc_u32 s11, s97, 0
	v_mov_b32_e32 v0, 0
	global_load_dword v0, v0, s[10:11] sc1
	s_waitcnt vmcnt(0)
	v_cmp_eq_u32_e32 vcc, v0, v1
	s_and_saveexec_b64 s[6:7], vcc
	s_cbranch_execz .LBB0_2781
	s_add_u32 s8, s96, 0x6fc200
	s_addc_u32 s9, s97, 0
	s_mov_b32 s24, 1
	s_mov_b64 s[14:15], 0
	v_mov_b32_e32 v0, 0
	s_branch .LBB0_2772

; __global__ void __launch_bounds__(512, 2) mega_all(Params p) {
	.amdhsa_kernel _Z8mega_all6Params
		.amdhsa_group_segment_fixed_size 0
		.amdhsa_private_segment_fixed_size 0
		.amdhsa_kernarg_size 536
		.amdhsa_user_sgpr_count 2
		.amdhsa_user_sgpr_dispatch_ptr 0
		.amdhsa_user_sgpr_queue_ptr 0
		.amdhsa_user_sgpr_kernarg_segment_ptr 1
		.amdhsa_user_sgpr_dispatch_id 0
		.amdhsa_user_sgpr_kernarg_preload_length 0
		.amdhsa_user_sgpr_kernarg_preload_offset 0
		.amdhsa_user_sgpr_private_segment_size 0
		.amdhsa_uses_dynamic_stack 0
		.amdhsa_enable_private_segment 0
		.amdhsa_system_sgpr_workgroup_id_x 1
		.amdhsa_system_sgpr_workgroup_id_y 0
		.amdhsa_system_sgpr_workgroup_id_z 0
		.amdhsa_system_sgpr_workgroup_info 0
		.amdhsa_system_vgpr_workitem_id 2
		.amdhsa_next_free_vgpr 250
		.amdhsa_next_free_sgpr 102
		.amdhsa_accum_offset 252
		.amdhsa_reserve_vcc 1
		.amdhsa_float_round_mode_32 0
		.amdhsa_float_round_mode_16_64 0
		.amdhsa_float_denorm_mode_32 3
		.amdhsa_float_denorm_mode_16_64 3
		.amdhsa_dx10_clamp 1
		.amdhsa_ieee_mode 1
		.amdhsa_fp16_overflow 0
		.amdhsa_tg_split 0
		.amdhsa_exception_fp_ieee_invalid_op 0
		.amdhsa_exception_fp_denorm_src 0
		.amdhsa_exception_fp_ieee_div_zero 0
		.amdhsa_exception_fp_ieee_overflow 0
		.amdhsa_exception_fp_ieee_underflow 0
		.amdhsa_exception_fp_ieee_inexact 0
		.amdhsa_exception_int_div_zero 0
	.end_amdhsa_kernel

; #define LAS __attribute__((address_space(3)))
; DEVI unsigned xb_add(unsigned* p, unsigned v) { return __hip_atomic_fetch_add(p, v, __ATOMIC_RELAXED, __HIP_MEMORY_SCOPE_AGENT); }
; DEVI unsigned xb_xcc_id() { return (unsigned)__builtin_amdgcn_s_getreg((3 << 11) | 20) & 0xFu; }
; __global__ void __launch_bounds__(512, 2) mega_all(Params p) {
;     extern __shared__ __attribute__((aligned(16))) unsigned char smem[];
;     cg::grid_group grid = cg::this_grid();
;     if (threadIdx.x < 4) ((LAS unsigned*)((LAS unsigned char*)smem + BAR_LDS_OFF))[threadIdx.x] = 0u;
;     __syncthreads();
;     if (threadIdx.x == 0) (void)xb_add(&((unsigned*)(p.ws + WS_BAR))[XB_XCNT(xb_xcc_id())], 1u);
;     run_range<0, N_PHASES>(p, smem, grid);
; }
amdhsa.kernels:
  - .agpr_count:     0
    .args:
      - .offset:         0
        .size:           280
        .value_kind:     by_value
      - .offset:         280
        .size:           4
        .value_kind:     hidden_block_count_x
      - .offset:         284
        .size:           4
        .value_kind:     hidden_block_count_y
      - .offset:         288
        .size:           4
        .value_kind:     hidden_block_count_z
      - .offset:         292
        .size:           2
        .value_kind:     hidden_group_size_x
      - .offset:         294
        .size:           2
        .value_kind:     hidden_group_size_y
      - .offset:         296
        .size:           2
        .value_kind:     hidden_group_size_z
      - .offset:         298
        .size:           2
        .value_kind:     hidden_remainder_x
      - .offset:         300
        .size:           2
        .value_kind:     hidden_remainder_y
      - .offset:         302
        .size:           2
        .value_kind:     hidden_remainder_z
      - .offset:         320
        .size:           8
        .value_kind:     hidden_global_offset_x
      - .offset:         328
        .size:           8
        .value_kind:     hidden_global_offset_y
      - .offset:         336
        .size:           8
        .value_kind:     hidden_global_offset_z
      - .offset:         344
        .size:           2
        .value_kind:     hidden_grid_dims
      - .offset:         368
        .size:           8
        .value_kind:     hidden_multigrid_sync_arg
      - .offset:         400
        .size:           4
        .value_kind:     hidden_dynamic_lds_size
    .group_segment_fixed_size: 0
    .kernarg_segment_align: 8
    .kernarg_segment_size: 536
    .language:       OpenCL C
    .language_version:
      - 2
      - 0
    .max_flat_workgroup_size: 512
    .name:           _Z8mega_all6Params
    .private_segment_fixed_size: 0
    .sgpr_count:     108
    .sgpr_spill_count: 79
    .symbol:         _Z8mega_all6Params.kd
    .uniform_work_group_size: 1
    .uses_dynamic_stack: false
    .vgpr_count:     250
    .vgpr_spill_count: 0
    .wavefront_size: 64
